# v35 + LRU-1 PRM load overlap + P5 out-projection: contiguous-64-column wave mapping and full-128B-line OUTB stores
# speedup vs baseline: 1.0106x; 1.0041x over previous
; #define PG8_STAGE(bufoff, gbase, voff) do { _Pragma("unroll") for (int _i = 0; _i < 2; ++_i) \
;         __builtin_amdgcn_global_load_lds((const unsigned*)((const char*)(gbase) + (voff)[_i]), (PG8_LAS unsigned*)(lds + (bufoff) + ldsw + _i * 8192), 16, 0, 0); } while (0)
; #define PG8_WAIT_V(n) asm volatile("s_waitcnt vmcnt(" #n ")" ::: "memory")
; #define PG8_BAR __builtin_amdgcn_s_barrier()
; template <class Epi, class Sched>
; __device__ __forceinline__ void gemm_phase(PG8_LAS unsigned char* lds, const Gemm g, const Sched& S, const Epi& E) {
;     ...
;     for (int i = 0; i < 2; ++i) { int R, C; stage_rc(tid * 16 + i * 8192, R, C); const int Rb = (R & ~31) + perm32(R & 31);
;         voffA[i] = (unsigned)(R * g.lda + C) * 2u; voffB[i] = (unsigned)(Rb * g.ldb + C) * 2u; }
;     const size_t kstep = (size_t)(BK * 2);
;     const size_t hstepA = (size_t)HALF * g.lda * 2, hstepB = (size_t)HALF * g.ldb * 2;
;     const unsigned ldsw = (unsigned)wid * 1024u;
;     const int aoff = lds_byte(wr * 64 + fr, fq * 8), boff = lds_byte(wc * 32 + fr, fq * 8);
;     ...
;     Unit cur, nxt; int ui = 0;
;     if (!S.next(0, cur)) return;
;     f32x4 acc[2][2][4][2];
; #pragma unroll
;     for (int a = 0; a < 2; ++a)
; #pragma unroll
;         for (int b = 0; b < 2; ++b)
; #pragma unroll
;             for (int m = 0; m < 4; ++m)
; #pragma unroll
;                 for (int n = 0; n < 2; ++n) acc[a][b][m][n] = (f32x4){0.f, 0.f, 0.f, 0.f};
;     bf16x8 At[4][2], B0[2][2], B1[2][2];
;     const char* cA = (const char*)cur.A; const char* cB = (const char*)cur.B;
;     PG8_STAGE(PG8_SB(0, 0), cB, voffB); PG8_STAGE(PG8_SB(0, 1), cB + hstepB, voffB); PG8_STAGE(PG8_SA(0, 0), cA, voffA); PG8_STAGE(PG8_SA(0, 1), cA + hstepA, voffA);
;     if (wr == 1) PG8_BAR;
;     PG8_WAIT_V(2); PG8_BAR;
;     PG8_STAGE(PG8_SB(1, 0), cB + kstep, voffB); PG8_STAGE(PG8_SA(1, 0), cA + kstep, voffA); PG8_STAGE(PG8_SB(1, 1), cB + hstepB + kstep, voffB);
;     PG8_WAIT_V(6); PG8_BAR;
.LBB0_940:
	v_ashrrev_i32_e32 v0, 31, v10
	v_lshrrev_b32_e32 v0, 26, v0
	v_add_u32_e32 v0, v10, v0
	v_ashrrev_i32_e32 v11, 6, v0
	v_bfe_i32 v0, v10, 27, 1
	v_lshlrev_b32_e32 v2, 4, v10
	v_lshrrev_b32_e32 v0, 22, v0
	v_add_u32_e32 v0, v2, v0
	v_and_b32_e32 v0, 0xfffffc00, v0
	v_sub_u32_e32 v0, v2, v0
	v_lshrrev_b32_e32 v3, 4, v0
	v_bitop3_b32 v0, v3, v0, 32 bitop3:0x6c
	v_ashrrev_i32_e32 v4, 31, v0
	v_lshrrev_b32_e32 v4, 26, v4
	v_add_u32_e32 v4, v0, v4
	v_lshlrev_b32_e32 v3, 3, v11
	v_ashrrev_i32_e32 v12, 6, v4
	v_and_b32_e32 v4, 0xc0, v4
	v_and_b32_e32 v3, -16, v3
	v_sub_u32_e32 v0, v0, v4
	v_add_u32_e32 v3, v12, v3
	v_ashrrev_i16_sdwa v0, v230, sext(v0) dst_sel:DWORD dst_unused:UNUSED_PAD src0_sel:DWORD src1_sel:BYTE_0
	v_lshlrev_b32_e32 v5, 5, v11
	v_bfe_i32 v13, v0, 0, 16
	v_lshlrev_b32_e32 v0, 1, v3
	v_lshrrev_b32_e32 v4, 2, v3
	v_and_b32_e32 v6, 3, v12
	s_mov_b32 s5, 0x1fffe0
	v_and_b32_e32 v5, 32, v5
	v_and_b32_e32 v0, 24, v0
	v_and_b32_e32 v4, 4, v4
	v_and_or_b32 v6, v3, s5, v6
	v_or3_b32 v0, v6, v4, v0
	v_add_lshl_u32 v4, v5, v13, 1
	v_add_u32_e32 v2, 0x2000, v2
	v_lshl_add_u32 v130, v3, 11, v4
	v_ashrrev_i32_e32 v3, 31, v2
	v_lshrrev_b32_e32 v3, 22, v3
	v_add_u32_e32 v3, v2, v3
	v_ashrrev_i32_e32 v14, 10, v3
	v_mul_i32_i24_e32 v3, 0x400, v14
	v_sub_u32_e32 v2, v2, v3
	v_lshrrev_b32_e32 v3, 4, v2
	v_bitop3_b32 v2, v3, v2, 32 bitop3:0x6c
	v_lshl_add_u32 v0, v0, 11, v4
	v_ashrrev_i32_e32 v4, 31, v2
	v_lshrrev_b32_e32 v4, 26, v4
	v_add_u32_e32 v4, v2, v4
	v_lshlrev_b32_e32 v3, 3, v14
	v_ashrrev_i32_e32 v15, 6, v4
	v_and_b32_e32 v4, 0xc0, v4
	s_ashr_i32 s4, s2, 6
	v_and_b32_e32 v3, -16, v3
	v_sub_u32_e32 v2, v2, v4
	v_add_u32_e32 v3, v15, v3
	v_ashrrev_i16_sdwa v2, v230, sext(v2) dst_sel:DWORD dst_unused:UNUSED_PAD src0_sel:DWORD src1_sel:BYTE_0
	s_lshl_b32 s9, s4, 10
	v_lshlrev_b32_e32 v5, 5, v14
	v_bfe_i32 v16, v2, 0, 16
	v_lshlrev_b32_e32 v2, 1, v3
	v_lshrrev_b32_e32 v4, 2, v3
	v_and_b32_e32 v6, 3, v15
	s_add_i32 s57, s9, 0
	v_and_b32_e32 v5, 32, v5
	v_and_b32_e32 v2, 24, v2
	v_and_b32_e32 v4, 4, v4
	v_and_or_b32 v6, v3, s5, v6
	s_add_i32 m0, s57, 0x10000
	v_or3_b32 v2, v6, v4, v2
	v_add_lshl_u32 v4, v5, v16, 1
	s_ashr_i32 s5, s2, 8
	s_lshl_b32 s99, s5, 16
	v_add_u32_e32 v0, s99, v0
	global_load_lds_dwordx4 v0, s[50:51]
	s_add_i32 m0, s57, 0x12000
	v_lshl_add_u32 v134, v2, 11, v4
	s_add_i32 s99, s99, 0x20000
	v_add_u32_e32 v134, s99, v134
	s_add_u32 s12, s50, 0x10000
	global_load_lds_dwordx4 v134, s[50:51]
	s_addc_u32 s13, s51, 0
	s_add_i32 m0, s57, 0x14000
	s_add_i32 s58, s57, 0x2000
	global_load_lds_dwordx4 v0, s[12:13]
	s_add_i32 m0, s57, 0x16000
	v_lshl_add_u32 v132, v3, 11, v4
	global_load_lds_dwordx4 v134, s[12:13]
	s_mov_b32 m0, s57
	s_add_u32 s12, s48, 0x40000
	global_load_lds_dwordx4 v130, s[48:49]
	s_mov_b32 m0, s58
	s_addc_u32 s13, s49, 0
	s_add_i32 s59, s57, 0x4000
	global_load_lds_dwordx4 v132, s[48:49]
	s_mov_b32 m0, s59
	s_add_i32 s60, s57, 0x6000
	global_load_lds_dwordx4 v130, s[12:13]
	s_mov_b32 m0, s60
	v_mov_b32_e32 v135, v1
	global_load_lds_dwordx4 v132, s[12:13]
	v_mov_b32_e32 v131, v1
	v_mov_b32_e32 v133, v1
	s_cmp_eq_u32 s5, 1
	v_lshl_add_u64 v[8:9], s[50:51], 0, v[0:1]
	v_lshl_add_u64 v[6:7], s[50:51], 0, v[134:135]
	v_lshl_add_u64 v[2:3], s[48:49], 0, v[130:131]
	s_cselect_b64 s[12:13], -1, 0
	s_cmp_lg_u32 s5, 1
	v_lshl_add_u64 v[4:5], s[48:49], 0, v[132:133]
	s_cbranch_scc1 .LBB0_942
	s_barrier
.LBB0_942:
	s_and_b32 s61, s4, 3
	s_lshl_b32 s62, s5, 6
	s_lshl_b32 s18, s5, 13
	s_lshl_b32 s38, s61, 5
	s_lshl_b32 s39, s61, 12
	s_add_u32 s14, s36, 0x3800000
	s_addc_u32 s15, s37, 0
	s_add_i32 m0, s57, 0x18000
	v_lshl_add_u64 v[8:9], v[8:9], 0, s[20:21]
	s_waitcnt vmcnt(2)
	s_barrier
	global_load_lds_dwordx4 v[8:9], off
	v_lshl_add_u64 v[6:7], v[6:7], 0, s[20:21]
	s_add_i32 m0, s57, 0x1a000
	s_add_i32 s63, s57, 0x8000
	s_add_i32 s64, s57, 0xa000
	global_load_lds_dwordx4 v[6:7], off
	v_lshl_add_u64 v[2:3], v[2:3], 0, s[20:21]
	s_mov_b32 m0, s63
	s_add_u32 s4, s50, 0x10080
	global_load_lds_dwordx4 v[2:3], off
	v_lshl_add_u64 v[2:3], v[4:5], 0, s[20:21]
	s_mov_b32 m0, s64
	s_addc_u32 s5, s51, 0
	global_load_lds_dwordx4 v[2:3], off
	s_add_i32 m0, s57, 0x1c000
	v_lshl_add_u64 v[2:3], s[4:5], 0, v[0:1]
	global_load_lds_dwordx4 v[2:3], off
	v_lshl_add_u64 v[2:3], s[4:5], 0, v[134:135]
	s_add_i32 m0, s57, 0x1e000
	v_bfe_u32 v145, v10, 4, 2
	global_load_lds_dwordx4 v[2:3], off
	v_and_b32_e32 v144, 15, v10
	v_lshlrev_b32_e32 v2, 4, v145
	v_lshlrev_b32_e32 v3, 2, v10
	v_lshl_or_b32 v2, v144, 6, v2
	v_and_b32_e32 v3, 32, v3
	v_bitop3_b32 v4, v2, s18, v3 bitop3:0xde
	v_bitop3_b32 v146, v2, s39, v3 bitop3:0xde
	v_lshlrev_b32_e32 v2, 14, v11
	v_and_b32_e32 v2, 0xffff8000, v2
	v_lshl_add_u32 v2, v12, 11, v2
	v_and_b32_e32 v3, 1, v11
	v_lshl_or_b32 v2, v3, 6, v2
	v_lshl_add_u32 v136, v13, 1, v2
	v_lshlrev_b32_e32 v2, 14, v14
	v_and_b32_e32 v2, 0xffff8000, v2
	s_waitcnt vmcnt(6)
	v_lshl_add_u32 v2, v15, 11, v2
	v_and_b32_e32 v3, 1, v14
	s_cmpk_lt_u32 s2, 0x100
	v_lshl_or_b32 v2, v3, 6, v2
	s_cselect_b64 s[36:37], -1, 0
	s_ashr_i32 s65, s97, 31
	s_ashr_i32 s66, s96, 31
	v_mov_b32_e32 v137, v1
	v_lshl_add_u32 v138, v16, 1, v2
	v_mov_b32_e32 v139, v1
	s_mov_b32 s67, 0
	v_add_u32_e32 v147, 0, v4
	s_lshl_b32 s18, s38, 1
	s_mov_b64 s[42:43], s[48:49]
	s_mov_b64 s[44:45], s[50:51]
	s_barrier
	s_branch .LBB0_945

; #define PG8_STAGE(bufoff, gbase, voff) do { _Pragma("unroll") for (int _i = 0; _i < 2; ++_i) \
;         __builtin_amdgcn_global_load_lds((const unsigned*)((const char*)(gbase) + (voff)[_i]), (PG8_LAS unsigned*)(lds + (bufoff) + ldsw + _i * 8192), 16, 0, 0); } while (0)
; #define PG8_LDA(dst, b, h) do { _Pragma("unroll") for (int m = 0; m < 4; ++m) _Pragma("unroll") for (int k = 0; k < 2; ++k) dst[m][k] = *(const PG8_LAS bf16x8*)(lds + PG8_SA(b, h) + aoff + m * 2048 + k * 1024); } while (0)
; #define PG8_LDB(dst, b, h) do { _Pragma("unroll") for (int n = 0; n < 2; ++n) _Pragma("unroll") for (int k = 0; k < 2; ++k) dst[n][k] = *(const PG8_LAS bf16x8*)(lds + PG8_SB(b, h) + boff + n * 2048 + k * 1024); } while (0)
; #define PG8_MMA(ai, bj, At, Bt) do { __builtin_amdgcn_s_setprio(1); _Pragma("unroll") for (int m = 0; m < 4; ++m) _Pragma("unroll") for (int n = 0; n < 2; ++n) _Pragma("unroll") for (int k = 0; k < 2; ++k) \
;         acc[ai][bj][m][n] = __builtin_amdgcn_mfma_f32_16x16x32_bf16(Bt[n][k], At[m][k], acc[ai][bj][m][n], 0, 0, 0); __builtin_amdgcn_s_setprio(0); } while (0)
; #define PG8_WAIT_V(n) asm volatile("s_waitcnt vmcnt(" #n ")" ::: "memory")
; #define PG8_WAIT_L(n) asm volatile("s_waitcnt lgkmcnt(" #n ")" ::: "memory")
; #define PG8_BAR __builtin_amdgcn_s_barrier()
; #define PG8_SCHED __builtin_amdgcn_sched_barrier(0)
; template <class Epi, class Sched>
; __device__ __forceinline__ void gemm_phase(PG8_LAS unsigned char* lds, const Gemm g, const Sched& S, const Epi& E) {
;     ...
;         for (int t = 0; t < nt; t += 2) {
;             const bool last = (t == nt - 2);
;             const char* a1 = cA + (size_t)(t + 1) * kstep;
;             const char* a2 = last ? nA : cA + (size_t)(t + 2) * kstep; const char* b2 = last ? nB : cB + (size_t)(t + 2) * kstep;
;             const char* a3 = a2 + kstep; const char* b3 = b2 + kstep;
;             PG8_LDB(B0, 0, 0); PG8_LDB(B1, 0, 1); PG8_SCHED; PG8_LDA(At, 0, 0); PG8_STAGE(PG8_SA(1, 1), a1 + hstepA, voffA);
;             PG8_WAIT_V(8); PG8_WAIT_L(0); PG8_BAR; PG8_MMA(0, 0, At, B0); PG8_MMA(0, 1, At, B1); PG8_BAR; PG8_SCHED;
;             PG8_LDA(At, 0, 1); PG8_STAGE(PG8_SB(0, 0), b2, voffB); PG8_STAGE(PG8_SB(0, 1), b2 + hstepB, voffB); PG8_STAGE(PG8_SA(0, 0), a2, voffA);
;             PG8_WAIT_V(8); PG8_WAIT_L(0); PG8_BAR; PG8_MMA(1, 0, At, B0); PG8_MMA(1, 1, At, B1); PG8_BAR; PG8_SCHED;
.LBB0_952:
	s_add_u32 s50, s48, 0xfffc0080
	s_addc_u32 s51, s49, -1
	s_add_i32 s68, 0, 0x10000
	s_cmp_eq_u32 s41, 12
	s_cselect_b32 s53, s43, s51
	s_cselect_b32 s52, s42, s50
	s_cselect_b32 s51, s45, s39
	s_cselect_b32 s50, s44, s2
	s_add_i32 s70, 0, 0x14000
	v_add_u32_e32 v156, s68, v146
	v_add_u32_e32 v172, s70, v146
	ds_read_b128 v[140:143], v156
	ds_read_b128 v[148:151], v156 offset:1024
	ds_read_b128 v[152:155], v156 offset:2048
	ds_read_b128 v[156:159], v156 offset:3072
	ds_read_b128 v[160:163], v172
	ds_read_b128 v[164:167], v172 offset:1024
	ds_read_b128 v[168:171], v172 offset:2048
	ds_read_b128 v[172:175], v172 offset:3072
	v_lshl_add_u64 v[196:197], s[48:49], 0, v[136:137]
	s_add_i32 m0, s57, 0xc000
	ds_read_b128 v[176:179], v147
	ds_read_b128 v[180:183], v147 offset:1024
	ds_read_b128 v[184:187], v147 offset:2048
	ds_read_b128 v[188:191], v147 offset:3072
	ds_read_b128 v[192:195], v147 offset:4096
	ds_read_b128 v[202:205], v147 offset:5120
	ds_read_b128 v[206:209], v147 offset:6144
	ds_read_b128 v[210:213], v147 offset:7168
	global_load_lds_dwordx4 v[196:197], off
	v_lshl_add_u64 v[196:197], s[48:49], 0, v[138:139]
	s_add_i32 m0, s57, 0xe000
	s_nop 0
	global_load_lds_dwordx4 v[196:197], off
	s_waitcnt vmcnt(8)
	s_waitcnt lgkmcnt(0)
	s_barrier
	s_setprio 1
	s_waitcnt lgkmcnt(0)
	v_mfma_f32_16x16x32_bf16 v[126:129], v[140:143], v[176:179], v[126:129]
	v_mfma_f32_16x16x32_bf16 v[122:125], v[152:155], v[176:179], v[122:125]
	v_mfma_f32_16x16x32_bf16 v[110:113], v[140:143], v[184:187], v[110:113]
	v_mfma_f32_16x16x32_bf16 v[106:109], v[152:155], v[184:187], v[106:109]
	v_mfma_f32_16x16x32_bf16 v[94:97], v[140:143], v[192:195], v[94:97]
	v_mfma_f32_16x16x32_bf16 v[90:93], v[152:155], v[192:195], v[90:93]
	v_mfma_f32_16x16x32_bf16 v[78:81], v[140:143], v[206:209], v[78:81]
	v_mfma_f32_16x16x32_bf16 v[74:77], v[152:155], v[206:209], v[74:77]
	v_mfma_f32_16x16x32_bf16 v[126:129], v[148:151], v[180:183], v[126:129]
	v_mfma_f32_16x16x32_bf16 v[122:125], v[156:159], v[180:183], v[122:125]
	v_mfma_f32_16x16x32_bf16 v[110:113], v[148:151], v[188:191], v[110:113]
	v_mfma_f32_16x16x32_bf16 v[106:109], v[156:159], v[188:191], v[106:109]
	v_mfma_f32_16x16x32_bf16 v[94:97], v[148:151], v[202:205], v[94:97]
	v_mfma_f32_16x16x32_bf16 v[90:93], v[156:159], v[202:205], v[90:93]
	v_mfma_f32_16x16x32_bf16 v[78:81], v[148:151], v[210:213], v[78:81]
	v_mfma_f32_16x16x32_bf16 v[74:77], v[156:159], v[210:213], v[74:77]
	s_setprio 0
	s_setprio 1
	v_mfma_f32_16x16x32_bf16 v[118:121], v[160:163], v[176:179], v[118:121]
	v_mfma_f32_16x16x32_bf16 v[114:117], v[168:171], v[176:179], v[114:117]
	v_mfma_f32_16x16x32_bf16 v[102:105], v[160:163], v[184:187], v[102:105]
	v_mfma_f32_16x16x32_bf16 v[98:101], v[168:171], v[184:187], v[98:101]
	v_mfma_f32_16x16x32_bf16 v[86:89], v[160:163], v[192:195], v[86:89]
	v_mfma_f32_16x16x32_bf16 v[82:85], v[168:171], v[192:195], v[82:85]
	v_mfma_f32_16x16x32_bf16 v[70:73], v[160:163], v[206:209], v[70:73]
	v_mfma_f32_16x16x32_bf16 v[66:69], v[168:171], v[206:209], v[66:69]
	v_mfma_f32_16x16x32_bf16 v[118:121], v[164:167], v[180:183], v[118:121]
	v_mfma_f32_16x16x32_bf16 v[114:117], v[172:175], v[180:183], v[114:117]
	v_mfma_f32_16x16x32_bf16 v[102:105], v[164:167], v[188:191], v[102:105]
	v_mfma_f32_16x16x32_bf16 v[98:101], v[172:175], v[188:191], v[98:101]
	v_mfma_f32_16x16x32_bf16 v[86:89], v[164:167], v[202:205], v[86:89]
	v_mfma_f32_16x16x32_bf16 v[82:85], v[172:175], v[202:205], v[82:85]
	v_mfma_f32_16x16x32_bf16 v[70:73], v[164:167], v[210:213], v[70:73]
	v_mfma_f32_16x16x32_bf16 v[66:69], v[172:175], v[210:213], v[66:69]
	s_setprio 0
	s_barrier
	s_add_i32 s68, s68, s9
	v_lshl_add_u64 v[196:197], s[50:51], 0, v[0:1]
	s_mov_b32 m0, s68
	ds_read_b128 v[176:179], v147 offset:16384
	ds_read_b128 v[180:183], v147 offset:17408
	ds_read_b128 v[184:187], v147 offset:18432
	ds_read_b128 v[188:191], v147 offset:19456
	ds_read_b128 v[192:195], v147 offset:20480
	ds_read_b128 v[202:205], v147 offset:21504
	ds_read_b128 v[206:209], v147 offset:22528
	ds_read_b128 v[210:213], v147 offset:23552
	global_load_lds_dwordx4 v[196:197], off
	s_add_i32 m0, s68, 0x2000
	s_add_u32 s68, s50, 0x10000
	v_lshl_add_u64 v[198:199], s[50:51], 0, v[134:135]
	s_addc_u32 s69, s51, 0
	s_add_i32 s70, s70, s9
	global_load_lds_dwordx4 v[198:199], off
	v_lshl_add_u64 v[214:215], s[68:69], 0, v[0:1]
	s_mov_b32 m0, s70
	v_lshl_add_u64 v[216:217], s[52:53], 0, v[132:133]
	global_load_lds_dwordx4 v[214:215], off
	v_lshl_add_u64 v[214:215], s[68:69], 0, v[134:135]
	s_add_i32 m0, s70, 0x2000
	s_nop 0
	global_load_lds_dwordx4 v[214:215], off
	v_lshl_add_u64 v[214:215], s[52:53], 0, v[130:131]
	s_mov_b32 m0, s57
	s_nop 0
	global_load_lds_dwordx4 v[214:215], off
	s_mov_b32 m0, s58
	s_nop 0
	global_load_lds_dwordx4 v[216:217], off
	s_waitcnt vmcnt(8)
	s_waitcnt lgkmcnt(0)
	s_barrier
; #define PG8_STAGE(bufoff, gbase, voff) do { _Pragma("unroll") for (int _i = 0; _i < 2; ++_i) \
;         __builtin_amdgcn_global_load_lds((const unsigned*)((const char*)(gbase) + (voff)[_i]), (PG8_LAS unsigned*)(lds + (bufoff) + ldsw + _i * 8192), 16, 0, 0); } while (0)
; #define PG8_LDA(dst, b, h) do { _Pragma("unroll") for (int m = 0; m < 4; ++m) _Pragma("unroll") for (int k = 0; k < 2; ++k) dst[m][k] = *(const PG8_LAS bf16x8*)(lds + PG8_SA(b, h) + aoff + m * 2048 + k * 1024); } while (0)
; #define PG8_LDB(dst, b, h) do { _Pragma("unroll") for (int n = 0; n < 2; ++n) _Pragma("unroll") for (int k = 0; k < 2; ++k) dst[n][k] = *(const PG8_LAS bf16x8*)(lds + PG8_SB(b, h) + boff + n * 2048 + k * 1024); } while (0)
; #define PG8_MMA(ai, bj, At, Bt) do { __builtin_amdgcn_s_setprio(1); _Pragma("unroll") for (int m = 0; m < 4; ++m) _Pragma("unroll") for (int n = 0; n < 2; ++n) _Pragma("unroll") for (int k = 0; k < 2; ++k) \
;         acc[ai][bj][m][n] = __builtin_amdgcn_mfma_f32_16x16x32_bf16(Bt[n][k], At[m][k], acc[ai][bj][m][n], 0, 0, 0); __builtin_amdgcn_s_setprio(0); } while (0)
; #define PG8_WAIT_V(n) asm volatile("s_waitcnt vmcnt(" #n ")" ::: "memory")
; #define PG8_WAIT_L(n) asm volatile("s_waitcnt lgkmcnt(" #n ")" ::: "memory")
; #define PG8_BAR __builtin_amdgcn_s_barrier()
; #define PG8_SCHED __builtin_amdgcn_sched_barrier(0)
; template <class Epi, class Sched>
; __device__ __forceinline__ void gemm_phase(PG8_LAS unsigned char* lds, const Gemm g, const Sched& S, const Epi& E) {
;     ...
;             PG8_WAIT_V(8); PG8_WAIT_L(0); PG8_BAR; PG8_MMA(1, 0, At, B0); PG8_MMA(1, 1, At, B1); PG8_BAR; PG8_SCHED;
;             PG8_LDB(B0, 1, 0); PG8_LDB(B1, 1, 1); PG8_SCHED; PG8_LDA(At, 1, 0); PG8_STAGE(PG8_SA(0, 1), a2 + hstepA, voffA);
;             PG8_WAIT_V(8); PG8_WAIT_L(0); PG8_BAR; PG8_MMA(0, 0, At, B0); PG8_MMA(0, 1, At, B1); PG8_BAR; PG8_SCHED;
	s_setprio 1
	s_waitcnt lgkmcnt(0)
	v_mfma_f32_16x16x32_bf16 v[62:65], v[140:143], v[176:179], v[62:65]
	v_mfma_f32_16x16x32_bf16 v[58:61], v[152:155], v[176:179], v[58:61]
	v_mfma_f32_16x16x32_bf16 v[46:49], v[140:143], v[184:187], v[46:49]
	v_mfma_f32_16x16x32_bf16 v[42:45], v[152:155], v[184:187], v[42:45]
	v_mfma_f32_16x16x32_bf16 v[30:33], v[140:143], v[192:195], v[30:33]
	v_mfma_f32_16x16x32_bf16 v[26:29], v[152:155], v[192:195], v[26:29]
	v_mfma_f32_16x16x32_bf16 v[14:17], v[140:143], v[206:209], v[14:17]
	v_mfma_f32_16x16x32_bf16 v[10:13], v[152:155], v[206:209], v[10:13]
	v_mfma_f32_16x16x32_bf16 v[62:65], v[148:151], v[180:183], v[62:65]
	v_mfma_f32_16x16x32_bf16 v[58:61], v[156:159], v[180:183], v[58:61]
	v_mfma_f32_16x16x32_bf16 v[46:49], v[148:151], v[188:191], v[46:49]
	v_mfma_f32_16x16x32_bf16 v[42:45], v[156:159], v[188:191], v[42:45]
	v_mfma_f32_16x16x32_bf16 v[30:33], v[148:151], v[202:205], v[30:33]
	v_mfma_f32_16x16x32_bf16 v[26:29], v[156:159], v[202:205], v[26:29]
	v_mfma_f32_16x16x32_bf16 v[14:17], v[148:151], v[210:213], v[14:17]
	v_mfma_f32_16x16x32_bf16 v[10:13], v[156:159], v[210:213], v[10:13]
	s_setprio 0
	s_setprio 1
	v_mfma_f32_16x16x32_bf16 v[54:57], v[160:163], v[176:179], v[54:57]
	v_mfma_f32_16x16x32_bf16 v[50:53], v[168:171], v[176:179], v[50:53]
	v_mfma_f32_16x16x32_bf16 v[38:41], v[160:163], v[184:187], v[38:41]
	v_mfma_f32_16x16x32_bf16 v[34:37], v[168:171], v[184:187], v[34:37]
	v_mfma_f32_16x16x32_bf16 v[22:25], v[160:163], v[192:195], v[22:25]
	v_mfma_f32_16x16x32_bf16 v[18:21], v[168:171], v[192:195], v[18:21]
	v_mfma_f32_16x16x32_bf16 v[6:9], v[160:163], v[206:209], v[6:9]
	v_mfma_f32_16x16x32_bf16 v[2:5], v[168:171], v[206:209], v[2:5]
	v_mfma_f32_16x16x32_bf16 v[54:57], v[164:167], v[180:183], v[54:57]
	v_mfma_f32_16x16x32_bf16 v[50:53], v[172:175], v[180:183], v[50:53]
	v_mfma_f32_16x16x32_bf16 v[38:41], v[164:167], v[188:191], v[38:41]
	v_mfma_f32_16x16x32_bf16 v[34:37], v[172:175], v[188:191], v[34:37]
	v_mfma_f32_16x16x32_bf16 v[22:25], v[164:167], v[202:205], v[22:25]
	v_mfma_f32_16x16x32_bf16 v[18:21], v[172:175], v[202:205], v[18:21]
	v_mfma_f32_16x16x32_bf16 v[6:9], v[164:167], v[210:213], v[6:9]
	v_mfma_f32_16x16x32_bf16 v[2:5], v[172:175], v[210:213], v[2:5]
	s_setprio 0
	s_barrier
	s_add_i32 s68, 0, 0x18000
	s_add_i32 s69, 0, 0x1c000
	v_add_u32_e32 v156, s68, v146
	v_add_u32_e32 v172, s69, v146
	ds_read_b128 v[140:143], v156
	ds_read_b128 v[148:151], v156 offset:1024
	ds_read_b128 v[152:155], v156 offset:2048
	ds_read_b128 v[156:159], v156 offset:3072
	ds_read_b128 v[160:163], v172
	ds_read_b128 v[164:167], v172 offset:1024
	ds_read_b128 v[168:171], v172 offset:2048
	ds_read_b128 v[172:175], v172 offset:3072
	s_add_u32 s52, s52, 0x40000
	s_addc_u32 s53, s53, 0
	s_mov_b32 m0, s59
	v_lshl_add_u64 v[218:219], s[52:53], 0, v[130:131]
	ds_read_b128 v[176:179], v147 offset:32768
	ds_read_b128 v[180:183], v147 offset:33792
	ds_read_b128 v[184:187], v147 offset:34816
	ds_read_b128 v[188:191], v147 offset:35840
	ds_read_b128 v[192:195], v147 offset:36864
	ds_read_b128 v[202:205], v147 offset:37888
	ds_read_b128 v[206:209], v147 offset:38912
	ds_read_b128 v[210:213], v147 offset:39936
	global_load_lds_dwordx4 v[218:219], off
	v_lshl_add_u64 v[218:219], s[52:53], 0, v[132:133]
	s_mov_b32 m0, s60
	s_nop 0
	global_load_lds_dwordx4 v[218:219], off
	s_waitcnt vmcnt(8)
	s_waitcnt lgkmcnt(0)
	s_barrier
	s_setprio 1
	s_waitcnt lgkmcnt(0)
	v_mfma_f32_16x16x32_bf16 v[126:129], v[140:143], v[176:179], v[126:129]
	v_mfma_f32_16x16x32_bf16 v[122:125], v[152:155], v[176:179], v[122:125]
	v_mfma_f32_16x16x32_bf16 v[110:113], v[140:143], v[184:187], v[110:113]
	v_mfma_f32_16x16x32_bf16 v[106:109], v[152:155], v[184:187], v[106:109]
	v_mfma_f32_16x16x32_bf16 v[94:97], v[140:143], v[192:195], v[94:97]
	v_mfma_f32_16x16x32_bf16 v[90:93], v[152:155], v[192:195], v[90:93]
	v_mfma_f32_16x16x32_bf16 v[78:81], v[140:143], v[206:209], v[78:81]
	v_mfma_f32_16x16x32_bf16 v[74:77], v[152:155], v[206:209], v[74:77]
	v_mfma_f32_16x16x32_bf16 v[126:129], v[148:151], v[180:183], v[126:129]
	v_mfma_f32_16x16x32_bf16 v[122:125], v[156:159], v[180:183], v[122:125]
	v_mfma_f32_16x16x32_bf16 v[110:113], v[148:151], v[188:191], v[110:113]
	v_mfma_f32_16x16x32_bf16 v[106:109], v[156:159], v[188:191], v[106:109]
	v_mfma_f32_16x16x32_bf16 v[94:97], v[148:151], v[202:205], v[94:97]
	v_mfma_f32_16x16x32_bf16 v[90:93], v[156:159], v[202:205], v[90:93]
	v_mfma_f32_16x16x32_bf16 v[78:81], v[148:151], v[210:213], v[78:81]
	v_mfma_f32_16x16x32_bf16 v[74:77], v[156:159], v[210:213], v[74:77]
	s_setprio 0
	s_setprio 1
	v_mfma_f32_16x16x32_bf16 v[118:121], v[160:163], v[176:179], v[118:121]
	v_mfma_f32_16x16x32_bf16 v[114:117], v[168:171], v[176:179], v[114:117]
	v_mfma_f32_16x16x32_bf16 v[102:105], v[160:163], v[184:187], v[102:105]
	v_mfma_f32_16x16x32_bf16 v[98:101], v[168:171], v[184:187], v[98:101]
	v_mfma_f32_16x16x32_bf16 v[86:89], v[160:163], v[192:195], v[86:89]
	v_mfma_f32_16x16x32_bf16 v[82:85], v[168:171], v[192:195], v[82:85]
	v_mfma_f32_16x16x32_bf16 v[70:73], v[160:163], v[206:209], v[70:73]
	v_mfma_f32_16x16x32_bf16 v[66:69], v[168:171], v[206:209], v[66:69]
	v_mfma_f32_16x16x32_bf16 v[118:121], v[164:167], v[180:183], v[118:121]
	v_mfma_f32_16x16x32_bf16 v[114:117], v[172:175], v[180:183], v[114:117]
	v_mfma_f32_16x16x32_bf16 v[102:105], v[164:167], v[188:191], v[102:105]
	v_mfma_f32_16x16x32_bf16 v[98:101], v[172:175], v[188:191], v[98:101]
	v_mfma_f32_16x16x32_bf16 v[86:89], v[164:167], v[202:205], v[86:89]
	v_mfma_f32_16x16x32_bf16 v[82:85], v[172:175], v[202:205], v[82:85]
	v_mfma_f32_16x16x32_bf16 v[70:73], v[164:167], v[210:213], v[70:73]
	v_mfma_f32_16x16x32_bf16 v[66:69], v[172:175], v[210:213], v[66:69]
	s_setprio 0
	s_barrier
; #define PG8_STAGE(bufoff, gbase, voff) do { _Pragma("unroll") for (int _i = 0; _i < 2; ++_i) \
;         __builtin_amdgcn_global_load_lds((const unsigned*)((const char*)(gbase) + (voff)[_i]), (PG8_LAS unsigned*)(lds + (bufoff) + ldsw + _i * 8192), 16, 0, 0); } while (0)
; #define PG8_LDA(dst, b, h) do { _Pragma("unroll") for (int m = 0; m < 4; ++m) _Pragma("unroll") for (int k = 0; k < 2; ++k) dst[m][k] = *(const PG8_LAS bf16x8*)(lds + PG8_SA(b, h) + aoff + m * 2048 + k * 1024); } while (0)
; #define PG8_MMA(ai, bj, At, Bt) do { __builtin_amdgcn_s_setprio(1); _Pragma("unroll") for (int m = 0; m < 4; ++m) _Pragma("unroll") for (int n = 0; n < 2; ++n) _Pragma("unroll") for (int k = 0; k < 2; ++k) \
;         acc[ai][bj][m][n] = __builtin_amdgcn_mfma_f32_16x16x32_bf16(Bt[n][k], At[m][k], acc[ai][bj][m][n], 0, 0, 0); __builtin_amdgcn_s_setprio(0); } while (0)
; #define PG8_WAIT_V(n) asm volatile("s_waitcnt vmcnt(" #n ")" ::: "memory")
; #define PG8_WAIT_L(n) asm volatile("s_waitcnt lgkmcnt(" #n ")" ::: "memory")
; #define PG8_BAR __builtin_amdgcn_s_barrier()
; #define PG8_SCHED __builtin_amdgcn_sched_barrier(0)
; template <class Epi, class Sched>
; __device__ __forceinline__ void gemm_phase(PG8_LAS unsigned char* lds, const Gemm g, const Sched& S, const Epi& E) {
;     ...
;             PG8_LDA(At, 1, 1); PG8_STAGE(PG8_SB(1, 0), b3, voffB); PG8_STAGE(PG8_SB(1, 1), b3 + hstepB, voffB); PG8_STAGE(PG8_SA(1, 0), a3, voffA);
;             PG8_WAIT_V(8); PG8_WAIT_L(0); PG8_BAR; PG8_MMA(1, 0, At, B0); PG8_MMA(1, 1, At, B1); PG8_BAR; PG8_SCHED;
;         }
;         if (wr == 0) PG8_BAR;
;     __device__ __forceinline__ void operator()(f32x4 (&acc)[2][2][4][2], const Unit& u, int wr, int wc, int fr, int fq) const {
;     ...
;         bf16_t* base = u.O + (size_t)(wr * 64 + fr) * u.ldo + wc * 32 + 8 * fq;
; #pragma unroll
;         for (int ai = 0; ai < 2; ++ai)
; #pragma unroll
;             for (int m = 0; m < 4; ++m) { bf16_t* rowp = base + (size_t)(ai * HALF + m * 16) * u.ldo; float s = 0.f;
; #pragma unroll
;                 for (int bj = 0; bj < 2; ++bj) { const f32x4 v0 = acc[ai][bj][m][0], v1 = acc[ai][bj][m][1];
;                     s += (v0[0] * v0[0] + v0[1] * v0[1]) + (v0[2] * v0[2] + v0[3] * v0[3]) + (v1[0] * v1[0] + v1[1] * v1[1]) + (v1[2] * v1[2] + v1[3] * v1[3]);
;                     __builtin_nontemporal_store(pack8(v0, v1), (u32x4*)(rowp + bj * HALF)); }
	s_add_i32 s52, s68, s9
	v_lshl_add_u64 v[196:197], v[196:197], 0, s[20:21]
	s_mov_b32 m0, s52
	ds_read_b128 v[176:179], v147 offset:49152
	ds_read_b128 v[180:183], v147 offset:50176
	ds_read_b128 v[184:187], v147 offset:51200
	ds_read_b128 v[188:191], v147 offset:52224
	ds_read_b128 v[192:195], v147 offset:53248
	ds_read_b128 v[202:205], v147 offset:54272
	ds_read_b128 v[206:209], v147 offset:55296
	ds_read_b128 v[210:213], v147 offset:56320
	global_load_lds_dwordx4 v[196:197], off
	s_add_i32 m0, s52, 0x2000
	s_add_u32 s50, s50, 0x10080
	v_lshl_add_u64 v[196:197], v[198:199], 0, s[20:21]
	s_addc_u32 s51, s51, 0
	s_add_i32 s52, s69, s9
	global_load_lds_dwordx4 v[196:197], off
	v_lshl_add_u64 v[196:197], s[50:51], 0, v[0:1]
	s_mov_b32 m0, s52
	s_nop 0
	global_load_lds_dwordx4 v[196:197], off
	v_lshl_add_u64 v[196:197], s[50:51], 0, v[134:135]
	s_add_i32 m0, s52, 0x2000
	s_nop 0
	global_load_lds_dwordx4 v[196:197], off
	v_lshl_add_u64 v[196:197], v[214:215], 0, s[20:21]
	s_mov_b32 m0, s63
	s_nop 0
	global_load_lds_dwordx4 v[196:197], off
	v_lshl_add_u64 v[196:197], v[216:217], 0, s[20:21]
	s_mov_b32 m0, s64
	s_nop 0
	global_load_lds_dwordx4 v[196:197], off
	s_waitcnt vmcnt(8)
	s_waitcnt lgkmcnt(0)
	s_barrier
	s_setprio 1
	s_waitcnt lgkmcnt(0)
	v_mfma_f32_16x16x32_bf16 v[62:65], v[140:143], v[176:179], v[62:65]
	v_mfma_f32_16x16x32_bf16 v[58:61], v[152:155], v[176:179], v[58:61]
	v_mfma_f32_16x16x32_bf16 v[46:49], v[140:143], v[184:187], v[46:49]
	v_mfma_f32_16x16x32_bf16 v[42:45], v[152:155], v[184:187], v[42:45]
	v_mfma_f32_16x16x32_bf16 v[30:33], v[140:143], v[192:195], v[30:33]
	v_mfma_f32_16x16x32_bf16 v[26:29], v[152:155], v[192:195], v[26:29]
	v_mfma_f32_16x16x32_bf16 v[14:17], v[140:143], v[206:209], v[14:17]
	v_mfma_f32_16x16x32_bf16 v[10:13], v[152:155], v[206:209], v[10:13]
	v_mfma_f32_16x16x32_bf16 v[62:65], v[148:151], v[180:183], v[62:65]
	v_mfma_f32_16x16x32_bf16 v[58:61], v[156:159], v[180:183], v[58:61]
	v_mfma_f32_16x16x32_bf16 v[46:49], v[148:151], v[188:191], v[46:49]
	v_mfma_f32_16x16x32_bf16 v[42:45], v[156:159], v[188:191], v[42:45]
	v_mfma_f32_16x16x32_bf16 v[30:33], v[148:151], v[202:205], v[30:33]
	v_mfma_f32_16x16x32_bf16 v[26:29], v[156:159], v[202:205], v[26:29]
	v_mfma_f32_16x16x32_bf16 v[14:17], v[148:151], v[210:213], v[14:17]
	v_mfma_f32_16x16x32_bf16 v[10:13], v[156:159], v[210:213], v[10:13]
	s_setprio 0
	s_setprio 1
	v_mfma_f32_16x16x32_bf16 v[54:57], v[160:163], v[176:179], v[54:57]
	v_mfma_f32_16x16x32_bf16 v[50:53], v[168:171], v[176:179], v[50:53]
	v_mfma_f32_16x16x32_bf16 v[38:41], v[160:163], v[184:187], v[38:41]
	v_mfma_f32_16x16x32_bf16 v[34:37], v[168:171], v[184:187], v[34:37]
	v_mfma_f32_16x16x32_bf16 v[22:25], v[160:163], v[192:195], v[22:25]
	v_mfma_f32_16x16x32_bf16 v[18:21], v[168:171], v[192:195], v[18:21]
	v_mfma_f32_16x16x32_bf16 v[6:9], v[160:163], v[206:209], v[6:9]
	v_mfma_f32_16x16x32_bf16 v[2:5], v[168:171], v[206:209], v[2:5]
	v_mfma_f32_16x16x32_bf16 v[54:57], v[164:167], v[180:183], v[54:57]
	v_mfma_f32_16x16x32_bf16 v[50:53], v[172:175], v[180:183], v[50:53]
	v_mfma_f32_16x16x32_bf16 v[38:41], v[164:167], v[188:191], v[38:41]
	v_mfma_f32_16x16x32_bf16 v[34:37], v[172:175], v[188:191], v[34:37]
	v_mfma_f32_16x16x32_bf16 v[22:25], v[164:167], v[202:205], v[22:25]
	v_mfma_f32_16x16x32_bf16 v[18:21], v[172:175], v[202:205], v[18:21]
	v_mfma_f32_16x16x32_bf16 v[6:9], v[164:167], v[210:213], v[6:9]
	v_mfma_f32_16x16x32_bf16 v[2:5], v[172:175], v[210:213], v[2:5]
	s_setprio 0
	s_barrier
	s_add_i32 s41, s41, 2
	s_add_u32 s48, s48, 0x100
	s_addc_u32 s49, s49, 0
	s_add_u32 s2, s2, 0x100
	s_addc_u32 s39, s39, 0
	s_cmp_gt_u32 s41, 13
	s_cbranch_scc0 .LBB0_952
	s_and_b64 vcc, exec, s[36:37]
	s_cbranch_vccz .LBB0_955
	s_barrier
.LBB0_955:
	v_mov_b32_e32 v150, v145
	v_mov_b32_e32 v151, v144
	v_lshrrev_b32_e32 v242, 3, v144
	v_mul_i32_i24_e32 v242, 0xffffc040, v242
	s_lshl_b32 s48, s61, 6
	v_add_u32_e32 v242, s48, v242
	v_ashrrev_i32_e32 v243, 31, v242
	v_add_u32_e32 v244, 0x4000, v242
	v_mov_b32_e32 v245, 0
	s_nop 0
	v_add_u32_e32 v140, s62, v151
	v_ashrrev_i32_e32 v141, 31, v140
	v_lshlrev_b64 v[142:143], 11, v[140:141]
	v_lshl_add_u64 v[142:143], s[6:7], 0, v[142:143]
	v_lshlrev_b32_e32 v148, 3, v150
	v_lshl_add_u64 v[142:143], v[142:143], 0, s[18:19]
	v_ashrrev_i32_e32 v149, 31, v148
	v_lshlrev_b32_e32 v141, 2, v151
	v_lshl_add_u64 v[142:143], v[148:149], 1, v[142:143]
	v_lshl_add_u32 v141, v150, 6, v141
	v_cmp_eq_u32_e32 vcc, 0, v150
	v_mul_f32_e32 v149, v127, v127
	v_mul_f32_e32 v150, v129, v129
	v_fmac_f32_e32 v149, v126, v126
	v_fmac_f32_e32 v150, v128, v128
	v_cvt_pk_bf16_f32 v126, v126, v127
	v_cvt_pk_bf16_f32 v127, v128, v129
	v_mul_f32_e32 v128, v119, v119
	v_mul_f32_e32 v129, v121, v121
	v_fmac_f32_e32 v128, v118, v118
	v_fmac_f32_e32 v129, v120, v120
	v_add_f32_e32 v149, v149, v150
	v_mul_f32_e32 v150, v123, v123
	v_add_f32_e32 v128, v128, v129
	v_mul_f32_e32 v129, v115, v115
	v_fmac_f32_e32 v150, v122, v122
	v_fmac_f32_e32 v129, v114, v114
	v_add_f32_e32 v149, v149, v150
	v_mul_f32_e32 v150, v125, v125
	v_add_f32_e32 v128, v128, v129
	v_mul_f32_e32 v129, v117, v117
	v_fmac_f32_e32 v150, v124, v124
	v_fmac_f32_e32 v129, v116, v116
	v_add_f32_e32 v149, v150, v149
	v_add_f32_e32 v128, v129, v128
	v_xor_b32_e32 v148, 64, v141
	v_add_f32_e32 v149, v149, v128
	ds_bpermute_b32 v150, v148, v149
	v_xor_b32_e32 v141, 0x80, v141
	v_cvt_pk_bf16_f32 v128, v122, v123
	v_cvt_pk_bf16_f32 v129, v124, v125
	v_cvt_pk_bf16_f32 v122, v118, v119
	s_waitcnt lgkmcnt(0)
	v_add_f32_e32 v118, v149, v150
	ds_bpermute_b32 v119, v141, v118
	v_cvt_pk_bf16_f32 v123, v120, v121
	v_cvt_pk_bf16_f32 v124, v114, v115
	v_cvt_pk_bf16_f32 v125, v116, v117
	v_mov_b32_e32 v238, v122
	v_mov_b32_e32 v239, v123
	v_mov_b32_e32 v240, v124
	v_mov_b32_e32 v241, v125
	v_mov_b32_dpp v122, v126 row_ror:8 row_mask:0xf bank_mask:0x3
	v_mov_b32_dpp v123, v127 row_ror:8 row_mask:0xf bank_mask:0x3
	v_mov_b32_dpp v124, v128 row_ror:8 row_mask:0xf bank_mask:0x3
	v_mov_b32_dpp v125, v129 row_ror:8 row_mask:0xf bank_mask:0x3
	v_mov_b32_dpp v126, v238 row_ror:8 row_mask:0xf bank_mask:0xc
	v_mov_b32_dpp v127, v239 row_ror:8 row_mask:0xf bank_mask:0xc
	v_mov_b32_dpp v128, v240 row_ror:8 row_mask:0xf bank_mask:0xc
	v_mov_b32_dpp v129, v241 row_ror:8 row_mask:0xf bank_mask:0xc
	v_lshl_add_u64 v[246:247], v[142:143], 0, v[242:243]
	v_lshl_add_u64 v[248:249], v[142:143], 0, v[244:245]
	global_store_dwordx4 v[246:247], v[126:129], off nt
	global_store_dwordx4 v[248:249], v[122:125], off nt
	s_nop 1
	s_and_saveexec_b64 s[6:7], vcc
	s_cbranch_execz .LBB0_957
	v_add_u32_e32 v114, s8, v140
	v_ashrrev_i32_e32 v115, 31, v114
	s_lshl_b32 s48, s56, 2
	v_lshlrev_b64 v[114:115], 6, v[114:115]
	s_ashr_i32 s49, s48, 31
	v_lshl_add_u64 v[114:115], s[14:15], 0, v[114:115]
	v_lshl_add_u64 v[114:115], s[48:49], 2, v[114:115]
	s_lshl_b32 s48, s61, 2
	s_mov_b32 s49, s19
	s_waitcnt lgkmcnt(0)
	v_add_f32_e32 v116, v118, v119
	v_lshl_add_u64 v[114:115], v[114:115], 0, s[48:49]
	global_store_dword v[114:115], v116, off
; __device__ __forceinline__ float shx(float v, int lane, int m) { return __builtin_bit_cast(float, __builtin_amdgcn_ds_bpermute((lane ^ m) << 2, __builtin_bit_cast(int, v))); }
; __device__ __forceinline__ u32x4 pack8(const f32x4 v0, const f32x4 v1) { u32x4 w; w.x = cvt_pk_bf16(v0[0], v0[1]); w.y = cvt_pk_bf16(v0[2], v0[3]); w.z = cvt_pk_bf16(v1[0], v1[1]); w.w = cvt_pk_bf16(v1[2], v1[3]); return w; }
;     __device__ __forceinline__ void operator()(f32x4 (&acc)[2][2][4][2], const Unit& u, int wr, int wc, int fr, int fq) const {
;     ...
;         for (int ai = 0; ai < 2; ++ai)
; #pragma unroll
;             for (int m = 0; m < 4; ++m) { bf16_t* rowp = base + (size_t)(ai * HALF + m * 16) * u.ldo; float s = 0.f;
; #pragma unroll
;                 for (int bj = 0; bj < 2; ++bj) { const f32x4 v0 = acc[ai][bj][m][0], v1 = acc[ai][bj][m][1];
;                     s += (v0[0] * v0[0] + v0[1] * v0[1]) + (v0[2] * v0[2] + v0[3] * v0[3]) + (v1[0] * v1[0] + v1[1] * v1[1]) + (v1[2] * v1[2] + v1[3] * v1[3]);
;                     __builtin_nontemporal_store(pack8(v0, v1), (u32x4*)(rowp + bj * HALF)); }
;                 s += shx(s, lane_, 16); s += shx(s, lane_, 32);
;                 if (fq == 0) SSP[(size_t)(u.z + ai * HALF + wr * 64 + m * 16 + fr) * 16 + u.pn * 4 + wc] = s; }
.LBB0_957:
	s_or_b64 exec, exec, s[6:7]
	v_mul_f32_e32 v114, v111, v111
	v_mul_f32_e32 v115, v113, v113
	v_fmac_f32_e32 v114, v110, v110
	v_fmac_f32_e32 v115, v112, v112
	v_add_f32_e32 v114, v114, v115
	v_mul_f32_e32 v115, v107, v107
	v_fmac_f32_e32 v115, v106, v106
	v_cvt_pk_bf16_f32 v110, v110, v111
	v_cvt_pk_bf16_f32 v111, v112, v113
	v_cvt_pk_bf16_f32 v112, v106, v107
	v_mul_f32_e32 v106, v103, v103
	v_mul_f32_e32 v107, v105, v105
	v_fmac_f32_e32 v106, v102, v102
	v_fmac_f32_e32 v107, v104, v104
	v_add_f32_e32 v106, v106, v107
	v_mul_f32_e32 v107, v99, v99
	v_fmac_f32_e32 v107, v98, v98
	v_add_f32_e32 v114, v114, v115
	v_mul_f32_e32 v115, v109, v109
	v_add_f32_e32 v106, v106, v107
	v_mul_f32_e32 v107, v101, v101
	v_fmac_f32_e32 v115, v108, v108
	v_fmac_f32_e32 v107, v100, v100
	v_add_f32_e32 v114, v115, v114
	v_add_f32_e32 v106, v107, v106
	v_add_f32_e32 v107, v114, v106
	v_cvt_pk_bf16_f32 v113, v108, v109
	ds_bpermute_b32 v108, v148, v107
	v_add_co_u32_e64 v114, s[6:7], s79, v142
	s_nop 1
	v_addc_co_u32_e64 v115, s[6:7], 0, v143, s[6:7]
	v_cvt_pk_bf16_f32 v106, v102, v103
	s_waitcnt lgkmcnt(0)
	v_add_f32_e32 v102, v107, v108
	ds_bpermute_b32 v103, v141, v102
	v_cvt_pk_bf16_f32 v107, v104, v105
	v_cvt_pk_bf16_f32 v108, v98, v99
	v_cvt_pk_bf16_f32 v109, v100, v101
	v_mov_b32_e32 v238, v106
	v_mov_b32_e32 v239, v107
	v_mov_b32_e32 v240, v108
	v_mov_b32_e32 v241, v109
	v_mov_b32_dpp v106, v110 row_ror:8 row_mask:0xf bank_mask:0x3
	v_mov_b32_dpp v107, v111 row_ror:8 row_mask:0xf bank_mask:0x3
	v_mov_b32_dpp v108, v112 row_ror:8 row_mask:0xf bank_mask:0x3
	v_mov_b32_dpp v109, v113 row_ror:8 row_mask:0xf bank_mask:0x3
	v_mov_b32_dpp v110, v238 row_ror:8 row_mask:0xf bank_mask:0xc
	v_mov_b32_dpp v111, v239 row_ror:8 row_mask:0xf bank_mask:0xc
	v_mov_b32_dpp v112, v240 row_ror:8 row_mask:0xf bank_mask:0xc
	v_mov_b32_dpp v113, v241 row_ror:8 row_mask:0xf bank_mask:0xc
	v_lshl_add_u64 v[246:247], v[114:115], 0, v[242:243]
	v_lshl_add_u64 v[248:249], v[114:115], 0, v[244:245]
	global_store_dwordx4 v[246:247], v[110:113], off nt
	global_store_dwordx4 v[248:249], v[106:109], off nt
	s_nop 1
	s_and_saveexec_b64 s[6:7], vcc
	s_cbranch_execz .LBB0_959
	v_add3_u32 v98, s8, 16, v140
	v_ashrrev_i32_e32 v99, 31, v98
	s_lshl_b32 s48, s56, 2
	v_lshlrev_b64 v[98:99], 6, v[98:99]
	s_ashr_i32 s49, s48, 31
	v_lshl_add_u64 v[98:99], s[14:15], 0, v[98:99]
	v_lshl_add_u64 v[98:99], s[48:49], 2, v[98:99]
	s_lshl_b32 s48, s61, 2
	s_mov_b32 s49, s19
	s_waitcnt lgkmcnt(0)
	v_add_f32_e32 v100, v102, v103
	v_lshl_add_u64 v[98:99], v[98:99], 0, s[48:49]
	global_store_dword v[98:99], v100, off
.LBB0_959:
	s_or_b64 exec, exec, s[6:7]
	v_mul_f32_e32 v98, v95, v95
	v_mul_f32_e32 v99, v97, v97
	v_fmac_f32_e32 v98, v94, v94
	v_fmac_f32_e32 v99, v96, v96
	v_add_f32_e32 v98, v98, v99
	v_mul_f32_e32 v99, v91, v91
	v_fmac_f32_e32 v99, v90, v90
	v_cvt_pk_bf16_f32 v94, v94, v95
	v_cvt_pk_bf16_f32 v95, v96, v97
	v_cvt_pk_bf16_f32 v96, v90, v91
	v_mul_f32_e32 v90, v87, v87
	v_mul_f32_e32 v91, v89, v89
	v_fmac_f32_e32 v90, v86, v86
	v_fmac_f32_e32 v91, v88, v88
	v_add_f32_e32 v90, v90, v91
	v_mul_f32_e32 v91, v83, v83
	v_fmac_f32_e32 v91, v82, v82
	v_add_f32_e32 v98, v98, v99
	v_mul_f32_e32 v99, v93, v93
	v_add_f32_e32 v90, v90, v91
	v_mul_f32_e32 v91, v85, v85
	v_fmac_f32_e32 v99, v92, v92
	v_fmac_f32_e32 v91, v84, v84
	v_add_f32_e32 v98, v99, v98
	v_add_f32_e32 v90, v91, v90
	v_add_f32_e32 v91, v98, v90
	v_cvt_pk_bf16_f32 v97, v92, v93
	ds_bpermute_b32 v92, v148, v91
	v_add_co_u32_e64 v98, s[6:7], s27, v142
	s_nop 1
	v_addc_co_u32_e64 v99, s[6:7], 0, v143, s[6:7]
	v_cvt_pk_bf16_f32 v90, v86, v87
	s_waitcnt lgkmcnt(0)
	v_add_f32_e32 v86, v91, v92
	ds_bpermute_b32 v87, v141, v86
	v_cvt_pk_bf16_f32 v91, v88, v89
	v_cvt_pk_bf16_f32 v92, v82, v83
	v_cvt_pk_bf16_f32 v93, v84, v85
	v_mov_b32_e32 v238, v90
	v_mov_b32_e32 v239, v91
	v_mov_b32_e32 v240, v92
	v_mov_b32_e32 v241, v93
	v_mov_b32_dpp v90, v94 row_ror:8 row_mask:0xf bank_mask:0x3
	v_mov_b32_dpp v91, v95 row_ror:8 row_mask:0xf bank_mask:0x3
	v_mov_b32_dpp v92, v96 row_ror:8 row_mask:0xf bank_mask:0x3
	v_mov_b32_dpp v93, v97 row_ror:8 row_mask:0xf bank_mask:0x3
	v_mov_b32_dpp v94, v238 row_ror:8 row_mask:0xf bank_mask:0xc
	v_mov_b32_dpp v95, v239 row_ror:8 row_mask:0xf bank_mask:0xc
	v_mov_b32_dpp v96, v240 row_ror:8 row_mask:0xf bank_mask:0xc
	v_mov_b32_dpp v97, v241 row_ror:8 row_mask:0xf bank_mask:0xc
	v_lshl_add_u64 v[246:247], v[98:99], 0, v[242:243]
	v_lshl_add_u64 v[248:249], v[98:99], 0, v[244:245]
	global_store_dwordx4 v[246:247], v[94:97], off nt
	global_store_dwordx4 v[248:249], v[90:93], off nt
	s_nop 1
	s_and_saveexec_b64 s[6:7], vcc
	s_cbranch_execz .LBB0_961
	v_add3_u32 v82, s8, 32, v140
	v_ashrrev_i32_e32 v83, 31, v82
	s_lshl_b32 s48, s56, 2
	v_lshlrev_b64 v[82:83], 6, v[82:83]
	s_ashr_i32 s49, s48, 31
	v_lshl_add_u64 v[82:83], s[14:15], 0, v[82:83]
	v_lshl_add_u64 v[82:83], s[48:49], 2, v[82:83]
	s_lshl_b32 s48, s61, 2
	s_mov_b32 s49, s19
	s_waitcnt lgkmcnt(0)
	v_add_f32_e32 v84, v86, v87
	v_lshl_add_u64 v[82:83], v[82:83], 0, s[48:49]
	global_store_dword v[82:83], v84, off
; __device__ __forceinline__ float shx(float v, int lane, int m) { return __builtin_bit_cast(float, __builtin_amdgcn_ds_bpermute((lane ^ m) << 2, __builtin_bit_cast(int, v))); }
; __device__ __forceinline__ u32x4 pack8(const f32x4 v0, const f32x4 v1) { u32x4 w; w.x = cvt_pk_bf16(v0[0], v0[1]); w.y = cvt_pk_bf16(v0[2], v0[3]); w.z = cvt_pk_bf16(v1[0], v1[1]); w.w = cvt_pk_bf16(v1[2], v1[3]); return w; }
;     __device__ __forceinline__ void operator()(f32x4 (&acc)[2][2][4][2], const Unit& u, int wr, int wc, int fr, int fq) const {
;     ...
;         for (int ai = 0; ai < 2; ++ai)
; #pragma unroll
;             for (int m = 0; m < 4; ++m) { bf16_t* rowp = base + (size_t)(ai * HALF + m * 16) * u.ldo; float s = 0.f;
; #pragma unroll
;                 for (int bj = 0; bj < 2; ++bj) { const f32x4 v0 = acc[ai][bj][m][0], v1 = acc[ai][bj][m][1];
;                     s += (v0[0] * v0[0] + v0[1] * v0[1]) + (v0[2] * v0[2] + v0[3] * v0[3]) + (v1[0] * v1[0] + v1[1] * v1[1]) + (v1[2] * v1[2] + v1[3] * v1[3]);
;                     __builtin_nontemporal_store(pack8(v0, v1), (u32x4*)(rowp + bj * HALF)); }
;                 s += shx(s, lane_, 16); s += shx(s, lane_, 32);
;                 if (fq == 0) SSP[(size_t)(u.z + ai * HALF + wr * 64 + m * 16 + fr) * 16 + u.pn * 4 + wc] = s; }
.LBB0_961:
	s_or_b64 exec, exec, s[6:7]
	v_mul_f32_e32 v82, v79, v79
	v_mul_f32_e32 v83, v81, v81
	v_fmac_f32_e32 v82, v78, v78
	v_fmac_f32_e32 v83, v80, v80
	v_add_f32_e32 v82, v82, v83
	v_mul_f32_e32 v83, v75, v75
	v_fmac_f32_e32 v83, v74, v74
	v_cvt_pk_bf16_f32 v78, v78, v79
	v_cvt_pk_bf16_f32 v79, v80, v81
	v_cvt_pk_bf16_f32 v80, v74, v75
	v_mul_f32_e32 v74, v71, v71
	v_mul_f32_e32 v75, v73, v73
	v_fmac_f32_e32 v74, v70, v70
	v_fmac_f32_e32 v75, v72, v72
	v_add_f32_e32 v74, v74, v75
	v_mul_f32_e32 v75, v67, v67
	v_fmac_f32_e32 v75, v66, v66
	v_add_f32_e32 v82, v82, v83
	v_mul_f32_e32 v83, v77, v77
	v_add_f32_e32 v74, v74, v75
	v_mul_f32_e32 v75, v69, v69
	v_fmac_f32_e32 v83, v76, v76
	v_fmac_f32_e32 v75, v68, v68
	v_add_f32_e32 v82, v83, v82
	v_add_f32_e32 v74, v75, v74
	v_add_f32_e32 v75, v82, v74
	v_cvt_pk_bf16_f32 v81, v76, v77
	ds_bpermute_b32 v76, v148, v75
	v_add_co_u32_e64 v82, s[6:7], s78, v142
	s_nop 1
	v_addc_co_u32_e64 v83, s[6:7], 0, v143, s[6:7]
	v_cvt_pk_bf16_f32 v74, v70, v71
	s_waitcnt lgkmcnt(0)
	v_add_f32_e32 v70, v75, v76
	ds_bpermute_b32 v71, v141, v70
	v_cvt_pk_bf16_f32 v75, v72, v73
	v_cvt_pk_bf16_f32 v76, v66, v67
	v_cvt_pk_bf16_f32 v77, v68, v69
	v_mov_b32_e32 v238, v74
	v_mov_b32_e32 v239, v75
	v_mov_b32_e32 v240, v76
	v_mov_b32_e32 v241, v77
	v_mov_b32_dpp v74, v78 row_ror:8 row_mask:0xf bank_mask:0x3
	v_mov_b32_dpp v75, v79 row_ror:8 row_mask:0xf bank_mask:0x3
	v_mov_b32_dpp v76, v80 row_ror:8 row_mask:0xf bank_mask:0x3
	v_mov_b32_dpp v77, v81 row_ror:8 row_mask:0xf bank_mask:0x3
	v_mov_b32_dpp v78, v238 row_ror:8 row_mask:0xf bank_mask:0xc
	v_mov_b32_dpp v79, v239 row_ror:8 row_mask:0xf bank_mask:0xc
	v_mov_b32_dpp v80, v240 row_ror:8 row_mask:0xf bank_mask:0xc
	v_mov_b32_dpp v81, v241 row_ror:8 row_mask:0xf bank_mask:0xc
	v_lshl_add_u64 v[246:247], v[82:83], 0, v[242:243]
	v_lshl_add_u64 v[248:249], v[82:83], 0, v[244:245]
	global_store_dwordx4 v[246:247], v[78:81], off nt
	global_store_dwordx4 v[248:249], v[74:77], off nt
	s_nop 1
	s_and_saveexec_b64 s[6:7], vcc
	s_cbranch_execz .LBB0_963
	v_add3_u32 v66, s8, 48, v140
	v_ashrrev_i32_e32 v67, 31, v66
	s_lshl_b32 s48, s56, 2
	v_lshlrev_b64 v[66:67], 6, v[66:67]
	s_ashr_i32 s49, s48, 31
	v_lshl_add_u64 v[66:67], s[14:15], 0, v[66:67]
	v_lshl_add_u64 v[66:67], s[48:49], 2, v[66:67]
	s_lshl_b32 s48, s61, 2
	s_mov_b32 s49, s19
	s_waitcnt lgkmcnt(0)
	v_add_f32_e32 v68, v70, v71
	v_lshl_add_u64 v[66:67], v[66:67], 0, s[48:49]
	global_store_dword v[66:67], v68, off
.LBB0_963:
	s_or_b64 exec, exec, s[6:7]
	v_mul_f32_e32 v66, v63, v63
	v_mul_f32_e32 v67, v65, v65
	v_fmac_f32_e32 v66, v62, v62
	v_fmac_f32_e32 v67, v64, v64
	v_add_f32_e32 v66, v66, v67
	v_mul_f32_e32 v67, v59, v59
	v_fmac_f32_e32 v67, v58, v58
	v_cvt_pk_bf16_f32 v62, v62, v63
	v_cvt_pk_bf16_f32 v63, v64, v65
	v_cvt_pk_bf16_f32 v64, v58, v59
	v_mul_f32_e32 v58, v55, v55
	v_mul_f32_e32 v59, v57, v57
	v_fmac_f32_e32 v58, v54, v54
	v_fmac_f32_e32 v59, v56, v56
	v_add_f32_e32 v58, v58, v59
	v_mul_f32_e32 v59, v51, v51
	v_fmac_f32_e32 v59, v50, v50
	v_add_f32_e32 v66, v66, v67
	v_mul_f32_e32 v67, v61, v61
	v_add_f32_e32 v58, v58, v59
	v_mul_f32_e32 v59, v53, v53
	v_fmac_f32_e32 v67, v60, v60
	v_fmac_f32_e32 v59, v52, v52
	v_add_f32_e32 v66, v67, v66
	v_add_f32_e32 v58, v59, v58
	v_add_f32_e32 v59, v66, v58
	v_cvt_pk_bf16_f32 v65, v60, v61
	ds_bpermute_b32 v60, v148, v59
	v_add_co_u32_e64 v66, s[6:7], s80, v142
	s_nop 1
	v_addc_co_u32_e64 v67, s[6:7], 0, v143, s[6:7]
	v_cvt_pk_bf16_f32 v58, v54, v55
	s_waitcnt lgkmcnt(0)
	v_add_f32_e32 v54, v59, v60
	ds_bpermute_b32 v55, v141, v54
	v_cvt_pk_bf16_f32 v59, v56, v57
	v_cvt_pk_bf16_f32 v60, v50, v51
	v_cvt_pk_bf16_f32 v61, v52, v53
	v_mov_b32_e32 v238, v58
	v_mov_b32_e32 v239, v59
	v_mov_b32_e32 v240, v60
	v_mov_b32_e32 v241, v61
	v_mov_b32_dpp v58, v62 row_ror:8 row_mask:0xf bank_mask:0x3
	v_mov_b32_dpp v59, v63 row_ror:8 row_mask:0xf bank_mask:0x3
	v_mov_b32_dpp v60, v64 row_ror:8 row_mask:0xf bank_mask:0x3
	v_mov_b32_dpp v61, v65 row_ror:8 row_mask:0xf bank_mask:0x3
	v_mov_b32_dpp v62, v238 row_ror:8 row_mask:0xf bank_mask:0xc
	v_mov_b32_dpp v63, v239 row_ror:8 row_mask:0xf bank_mask:0xc
	v_mov_b32_dpp v64, v240 row_ror:8 row_mask:0xf bank_mask:0xc
	v_mov_b32_dpp v65, v241 row_ror:8 row_mask:0xf bank_mask:0xc
	v_lshl_add_u64 v[246:247], v[66:67], 0, v[242:243]
	v_lshl_add_u64 v[248:249], v[66:67], 0, v[244:245]
	global_store_dwordx4 v[246:247], v[62:65], off nt
	global_store_dwordx4 v[248:249], v[58:61], off nt
	s_nop 1
	s_and_saveexec_b64 s[6:7], vcc
	s_cbranch_execz .LBB0_965
	s_add_i32 s2, s8, 0x80
	v_add_u32_e32 v50, s2, v140
	v_ashrrev_i32_e32 v51, 31, v50
	s_lshl_b32 s48, s56, 2
	v_lshlrev_b64 v[50:51], 6, v[50:51]
	s_ashr_i32 s49, s48, 31
	v_lshl_add_u64 v[50:51], s[14:15], 0, v[50:51]
	v_lshl_add_u64 v[50:51], s[48:49], 2, v[50:51]
	s_lshl_b32 s48, s61, 2
	s_mov_b32 s49, s19
	s_waitcnt lgkmcnt(0)
	v_add_f32_e32 v52, v54, v55
	v_lshl_add_u64 v[50:51], v[50:51], 0, s[48:49]
	global_store_dword v[50:51], v52, off
; __device__ __forceinline__ float shx(float v, int lane, int m) { return __builtin_bit_cast(float, __builtin_amdgcn_ds_bpermute((lane ^ m) << 2, __builtin_bit_cast(int, v))); }
; __device__ __forceinline__ u32x4 pack8(const f32x4 v0, const f32x4 v1) { u32x4 w; w.x = cvt_pk_bf16(v0[0], v0[1]); w.y = cvt_pk_bf16(v0[2], v0[3]); w.z = cvt_pk_bf16(v1[0], v1[1]); w.w = cvt_pk_bf16(v1[2], v1[3]); return w; }
;     __device__ __forceinline__ void operator()(f32x4 (&acc)[2][2][4][2], const Unit& u, int wr, int wc, int fr, int fq) const {
;     ...
;         for (int ai = 0; ai < 2; ++ai)
; #pragma unroll
;             for (int m = 0; m < 4; ++m) { bf16_t* rowp = base + (size_t)(ai * HALF + m * 16) * u.ldo; float s = 0.f;
; #pragma unroll
;                 for (int bj = 0; bj < 2; ++bj) { const f32x4 v0 = acc[ai][bj][m][0], v1 = acc[ai][bj][m][1];
;                     s += (v0[0] * v0[0] + v0[1] * v0[1]) + (v0[2] * v0[2] + v0[3] * v0[3]) + (v1[0] * v1[0] + v1[1] * v1[1]) + (v1[2] * v1[2] + v1[3] * v1[3]);
;                     __builtin_nontemporal_store(pack8(v0, v1), (u32x4*)(rowp + bj * HALF)); }
;                 s += shx(s, lane_, 16); s += shx(s, lane_, 32);
;                 if (fq == 0) SSP[(size_t)(u.z + ai * HALF + wr * 64 + m * 16 + fr) * 16 + u.pn * 4 + wc] = s; }
.LBB0_965:
	s_or_b64 exec, exec, s[6:7]
	v_mul_f32_e32 v50, v47, v47
	v_mul_f32_e32 v51, v49, v49
	v_fmac_f32_e32 v50, v46, v46
	v_fmac_f32_e32 v51, v48, v48
	v_add_f32_e32 v50, v50, v51
	v_mul_f32_e32 v51, v43, v43
	v_fmac_f32_e32 v51, v42, v42
	v_cvt_pk_bf16_f32 v46, v46, v47
	v_cvt_pk_bf16_f32 v47, v48, v49
	v_cvt_pk_bf16_f32 v48, v42, v43
	v_mul_f32_e32 v42, v39, v39
	v_mul_f32_e32 v43, v41, v41
	v_fmac_f32_e32 v42, v38, v38
	v_fmac_f32_e32 v43, v40, v40
	v_add_f32_e32 v42, v42, v43
	v_mul_f32_e32 v43, v35, v35
	v_fmac_f32_e32 v43, v34, v34
	v_add_f32_e32 v50, v50, v51
	v_mul_f32_e32 v51, v45, v45
	v_add_f32_e32 v42, v42, v43
	v_mul_f32_e32 v43, v37, v37
	v_fmac_f32_e32 v51, v44, v44
	v_fmac_f32_e32 v43, v36, v36
	v_add_f32_e32 v50, v51, v50
	v_add_f32_e32 v42, v43, v42
	v_add_f32_e32 v43, v50, v42
	v_cvt_pk_bf16_f32 v49, v44, v45
	ds_bpermute_b32 v44, v148, v43
	v_add_co_u32_e64 v50, s[6:7], s81, v142
	s_nop 1
	v_addc_co_u32_e64 v51, s[6:7], 0, v143, s[6:7]
	v_cvt_pk_bf16_f32 v42, v38, v39
	s_waitcnt lgkmcnt(0)
	v_add_f32_e32 v38, v43, v44
	ds_bpermute_b32 v39, v141, v38
	v_cvt_pk_bf16_f32 v43, v40, v41
	v_cvt_pk_bf16_f32 v44, v34, v35
	v_cvt_pk_bf16_f32 v45, v36, v37
	v_mov_b32_e32 v238, v42
	v_mov_b32_e32 v239, v43
	v_mov_b32_e32 v240, v44
	v_mov_b32_e32 v241, v45
	v_mov_b32_dpp v42, v46 row_ror:8 row_mask:0xf bank_mask:0x3
	v_mov_b32_dpp v43, v47 row_ror:8 row_mask:0xf bank_mask:0x3
	v_mov_b32_dpp v44, v48 row_ror:8 row_mask:0xf bank_mask:0x3
	v_mov_b32_dpp v45, v49 row_ror:8 row_mask:0xf bank_mask:0x3
	v_mov_b32_dpp v46, v238 row_ror:8 row_mask:0xf bank_mask:0xc
	v_mov_b32_dpp v47, v239 row_ror:8 row_mask:0xf bank_mask:0xc
	v_mov_b32_dpp v48, v240 row_ror:8 row_mask:0xf bank_mask:0xc
	v_mov_b32_dpp v49, v241 row_ror:8 row_mask:0xf bank_mask:0xc
	v_lshl_add_u64 v[246:247], v[50:51], 0, v[242:243]
	v_lshl_add_u64 v[248:249], v[50:51], 0, v[244:245]
	global_store_dwordx4 v[246:247], v[46:49], off nt
	global_store_dwordx4 v[248:249], v[42:45], off nt
	s_nop 1
	s_and_saveexec_b64 s[6:7], vcc
	s_cbranch_execz .LBB0_967
	s_add_i32 s2, s8, 0x90
	v_add_u32_e32 v34, s2, v140
	v_ashrrev_i32_e32 v35, 31, v34
	s_lshl_b32 s48, s56, 2
	v_lshlrev_b64 v[34:35], 6, v[34:35]
	s_ashr_i32 s49, s48, 31
	v_lshl_add_u64 v[34:35], s[14:15], 0, v[34:35]
	v_lshl_add_u64 v[34:35], s[48:49], 2, v[34:35]
	s_lshl_b32 s48, s61, 2
	s_mov_b32 s49, s19
	s_waitcnt lgkmcnt(0)
	v_add_f32_e32 v36, v38, v39
	v_lshl_add_u64 v[34:35], v[34:35], 0, s[48:49]
	global_store_dword v[34:35], v36, off
; __device__ __forceinline__ float shx(float v, int lane, int m) { return __builtin_bit_cast(float, __builtin_amdgcn_ds_bpermute((lane ^ m) << 2, __builtin_bit_cast(int, v))); }
; __device__ __forceinline__ u32x4 pack8(const f32x4 v0, const f32x4 v1) { u32x4 w; w.x = cvt_pk_bf16(v0[0], v0[1]); w.y = cvt_pk_bf16(v0[2], v0[3]); w.z = cvt_pk_bf16(v1[0], v1[1]); w.w = cvt_pk_bf16(v1[2], v1[3]); return w; }
;     __device__ __forceinline__ void operator()(f32x4 (&acc)[2][2][4][2], const Unit& u, int wr, int wc, int fr, int fq) const {
;     ...
;         for (int ai = 0; ai < 2; ++ai)
; #pragma unroll
;             for (int m = 0; m < 4; ++m) { bf16_t* rowp = base + (size_t)(ai * HALF + m * 16) * u.ldo; float s = 0.f;
; #pragma unroll
;                 for (int bj = 0; bj < 2; ++bj) { const f32x4 v0 = acc[ai][bj][m][0], v1 = acc[ai][bj][m][1];
;                     s += (v0[0] * v0[0] + v0[1] * v0[1]) + (v0[2] * v0[2] + v0[3] * v0[3]) + (v1[0] * v1[0] + v1[1] * v1[1]) + (v1[2] * v1[2] + v1[3] * v1[3]);
;                     __builtin_nontemporal_store(pack8(v0, v1), (u32x4*)(rowp + bj * HALF)); }
;                 s += shx(s, lane_, 16); s += shx(s, lane_, 32);
;                 if (fq == 0) SSP[(size_t)(u.z + ai * HALF + wr * 64 + m * 16 + fr) * 16 + u.pn * 4 + wc] = s; }
.LBB0_967:
	s_or_b64 exec, exec, s[6:7]
	v_mul_f32_e32 v34, v31, v31
	v_mul_f32_e32 v35, v33, v33
	v_fmac_f32_e32 v34, v30, v30
	v_fmac_f32_e32 v35, v32, v32
	v_add_f32_e32 v34, v34, v35
	v_mul_f32_e32 v35, v27, v27
	v_fmac_f32_e32 v35, v26, v26
	v_cvt_pk_bf16_f32 v30, v30, v31
	v_cvt_pk_bf16_f32 v31, v32, v33
	v_cvt_pk_bf16_f32 v32, v26, v27
	v_mul_f32_e32 v26, v23, v23
	v_mul_f32_e32 v27, v25, v25
	v_fmac_f32_e32 v26, v22, v22
	v_fmac_f32_e32 v27, v24, v24
	v_add_f32_e32 v26, v26, v27
	v_mul_f32_e32 v27, v19, v19
	v_fmac_f32_e32 v27, v18, v18
	v_add_f32_e32 v34, v34, v35
	v_mul_f32_e32 v35, v29, v29
	v_add_f32_e32 v26, v26, v27
	v_mul_f32_e32 v27, v21, v21
	v_fmac_f32_e32 v35, v28, v28
	v_fmac_f32_e32 v27, v20, v20
	v_add_f32_e32 v34, v35, v34
	v_add_f32_e32 v26, v27, v26
	v_add_f32_e32 v27, v34, v26
	v_cvt_pk_bf16_f32 v33, v28, v29
	ds_bpermute_b32 v28, v148, v27
	v_add_co_u32_e64 v34, s[6:7], s82, v142
	s_nop 1
	v_addc_co_u32_e64 v35, s[6:7], 0, v143, s[6:7]
	v_cvt_pk_bf16_f32 v26, v22, v23
	s_waitcnt lgkmcnt(0)
	v_add_f32_e32 v22, v27, v28
	ds_bpermute_b32 v23, v141, v22
	v_cvt_pk_bf16_f32 v27, v24, v25
	v_cvt_pk_bf16_f32 v28, v18, v19
	v_cvt_pk_bf16_f32 v29, v20, v21
	v_mov_b32_e32 v238, v26
	v_mov_b32_e32 v239, v27
	v_mov_b32_e32 v240, v28
	v_mov_b32_e32 v241, v29
	v_mov_b32_dpp v26, v30 row_ror:8 row_mask:0xf bank_mask:0x3
	v_mov_b32_dpp v27, v31 row_ror:8 row_mask:0xf bank_mask:0x3
	v_mov_b32_dpp v28, v32 row_ror:8 row_mask:0xf bank_mask:0x3
	v_mov_b32_dpp v29, v33 row_ror:8 row_mask:0xf bank_mask:0x3
	v_mov_b32_dpp v30, v238 row_ror:8 row_mask:0xf bank_mask:0xc
	v_mov_b32_dpp v31, v239 row_ror:8 row_mask:0xf bank_mask:0xc
	v_mov_b32_dpp v32, v240 row_ror:8 row_mask:0xf bank_mask:0xc
	v_mov_b32_dpp v33, v241 row_ror:8 row_mask:0xf bank_mask:0xc
	v_lshl_add_u64 v[246:247], v[34:35], 0, v[242:243]
	v_lshl_add_u64 v[248:249], v[34:35], 0, v[244:245]
	global_store_dwordx4 v[246:247], v[30:33], off nt
	global_store_dwordx4 v[248:249], v[26:29], off nt
	s_nop 1
	s_and_saveexec_b64 s[6:7], vcc
	s_cbranch_execz .LBB0_969
	s_add_i32 s2, s8, 0xa0
	v_add_u32_e32 v18, s2, v140
	v_ashrrev_i32_e32 v19, 31, v18
	s_lshl_b32 s48, s56, 2
	v_lshlrev_b64 v[18:19], 6, v[18:19]
	s_ashr_i32 s49, s48, 31
	v_lshl_add_u64 v[18:19], s[14:15], 0, v[18:19]
	v_lshl_add_u64 v[18:19], s[48:49], 2, v[18:19]
	s_lshl_b32 s48, s61, 2
	s_mov_b32 s49, s19
	s_waitcnt lgkmcnt(0)
	v_add_f32_e32 v20, v22, v23
	v_lshl_add_u64 v[18:19], v[18:19], 0, s[48:49]
	global_store_dword v[18:19], v20, off
.LBB0_969:
	s_or_b64 exec, exec, s[6:7]
	v_mul_f32_e32 v18, v15, v15
	v_mul_f32_e32 v19, v17, v17
	v_fmac_f32_e32 v18, v14, v14
	v_fmac_f32_e32 v19, v16, v16
	v_add_f32_e32 v18, v18, v19
	v_mul_f32_e32 v19, v11, v11
	v_fmac_f32_e32 v19, v10, v10
	v_cvt_pk_bf16_f32 v14, v14, v15
	v_cvt_pk_bf16_f32 v15, v16, v17
	v_cvt_pk_bf16_f32 v16, v10, v11
	v_mul_f32_e32 v10, v7, v7
	v_mul_f32_e32 v11, v9, v9
	v_fmac_f32_e32 v10, v6, v6
	v_fmac_f32_e32 v11, v8, v8
	v_add_f32_e32 v10, v10, v11
	v_mul_f32_e32 v11, v3, v3
	v_fmac_f32_e32 v11, v2, v2
	v_add_f32_e32 v18, v18, v19
	v_mul_f32_e32 v19, v13, v13
	v_add_f32_e32 v10, v10, v11
	v_mul_f32_e32 v11, v5, v5
	v_fmac_f32_e32 v19, v12, v12
	v_fmac_f32_e32 v11, v4, v4
	v_add_f32_e32 v18, v19, v18
	v_add_f32_e32 v10, v11, v10
	v_add_f32_e32 v11, v18, v10
	v_cvt_pk_bf16_f32 v17, v12, v13
	ds_bpermute_b32 v12, v148, v11
	v_add_co_u32_e64 v18, s[6:7], s83, v142
	s_nop 1
	v_addc_co_u32_e64 v19, s[6:7], 0, v143, s[6:7]
	v_cvt_pk_bf16_f32 v10, v6, v7
	s_waitcnt lgkmcnt(0)
	v_add_f32_e32 v6, v11, v12
	ds_bpermute_b32 v7, v141, v6
	v_cvt_pk_bf16_f32 v11, v8, v9
	v_cvt_pk_bf16_f32 v12, v2, v3
	v_cvt_pk_bf16_f32 v13, v4, v5
	v_mov_b32_e32 v238, v10
	v_mov_b32_e32 v239, v11
	v_mov_b32_e32 v240, v12
	v_mov_b32_e32 v241, v13
	v_mov_b32_dpp v10, v14 row_ror:8 row_mask:0xf bank_mask:0x3
	v_mov_b32_dpp v11, v15 row_ror:8 row_mask:0xf bank_mask:0x3
	v_mov_b32_dpp v12, v16 row_ror:8 row_mask:0xf bank_mask:0x3
	v_mov_b32_dpp v13, v17 row_ror:8 row_mask:0xf bank_mask:0x3
	v_mov_b32_dpp v14, v238 row_ror:8 row_mask:0xf bank_mask:0xc
	v_mov_b32_dpp v15, v239 row_ror:8 row_mask:0xf bank_mask:0xc
	v_mov_b32_dpp v16, v240 row_ror:8 row_mask:0xf bank_mask:0xc
	v_mov_b32_dpp v17, v241 row_ror:8 row_mask:0xf bank_mask:0xc
	v_lshl_add_u64 v[246:247], v[18:19], 0, v[242:243]
	v_lshl_add_u64 v[248:249], v[18:19], 0, v[244:245]
	global_store_dwordx4 v[246:247], v[14:17], off nt
	global_store_dwordx4 v[248:249], v[10:13], off nt
	s_nop 1
	s_and_saveexec_b64 s[6:7], vcc
	s_cbranch_execz .LBB0_971
	s_add_i32 s2, s8, 0xb0
	v_add_u32_e32 v2, s2, v140
	v_ashrrev_i32_e32 v3, 31, v2
	s_lshl_b32 s48, s56, 2
	v_lshlrev_b64 v[2:3], 6, v[2:3]
	s_ashr_i32 s49, s48, 31
	v_lshl_add_u64 v[2:3], s[14:15], 0, v[2:3]
	v_lshl_add_u64 v[2:3], s[48:49], 2, v[2:3]
	s_lshl_b32 s48, s61, 2
	s_mov_b32 s49, s19
	s_waitcnt lgkmcnt(0)
	v_add_f32_e32 v4, v6, v7
	v_lshl_add_u64 v[2:3], v[2:3], 0, s[48:49]
	global_store_dword v[2:3], v4, off
